# softmax groups re-spaced by cost weight: v_exp interleaved with the v_sub of the same 8-wide group instead of 8 transcendentals back to back
# baseline (speedup 1.0000x reference)
; #define LAS __attribute__((address_space(3)))
; __device__ __forceinline__ unsigned pk2(float lo, float hi) { f32x2 v = {lo, hi}; bf16x2_t b = __builtin_convertvector(v, bf16x2_t); return __builtin_bit_cast(unsigned, b); }
; #define MFMA32(a, b, c) __builtin_amdgcn_mfma_f32_32x32x16_bf16((a), (b), (c), 0, 0, 0)
; __device__ __forceinline__ void unit(LAS unsigned char* lds, const Tensors& T, int h, int qrow0, int nact, bool sample, int limbase, int kv0, int kvnew, int nt) {
;     ...
;             { float ps = 0.f;
; #pragma unroll
;               for (int r = 0; r < 16; ++r) { p0[r] = __builtin_amdgcn_exp2f(p0[r] - mrun); p1[r] = __builtin_amdgcn_exp2f(p1[r] - mrun); ps += p0[r] + p1[r]; }
;               lrun += ps; }
;             const LAS unsigned char* vp = lds + OFF_V + buf * VBUF + r32 * VP + hi * 16;
;             { u32x4 vf[2][4];
; #pragma unroll
;               for (int d = 0; d < 4; ++d) vf[0][d] = *(const LAS u32x4*)(vp + d * 32 * VP);
; #pragma unroll
;               for (int j = 0; j < 4; ++j) {
;                   if (j < 3) {
; #pragma unroll
;                       for (int d = 0; d < 4; ++d) vf[(j + 1) & 1][d] = *(const LAS u32x4*)(vp + d * 32 * VP + (j + 1) * 32); }
;                   u32x4 pw;
;                   if (j == 0) { pw.x = pk2(p0[0], p0[1]); pw.y = pk2(p0[2], p0[3]); pw.z = pk2(p0[4], p0[5]); pw.w = pk2(p0[6], p0[7]); }
;                   else if (j == 1) { pw.x = pk2(p0[8], p0[9]); pw.y = pk2(p0[10], p0[11]); pw.z = pk2(p0[12], p0[13]); pw.w = pk2(p0[14], p0[15]); }
;                   else if (j == 2) { pw.x = pk2(p1[0], p1[1]); pw.y = pk2(p1[2], p1[3]); pw.z = pk2(p1[4], p1[5]); pw.w = pk2(p1[6], p1[7]); }
;                   else { pw.x = pk2(p1[8], p1[9]); pw.y = pk2(p1[10], p1[11]); pw.z = pk2(p1[12], p1[13]); pw.w = pk2(p1[14], p1[15]); }
;                   const bf16x8 pa = __builtin_bit_cast(bf16x8, pw);
;                   __builtin_amdgcn_sched_barrier(0);
; #pragma unroll
;                   for (int d = 0; d < 4; ++d) o[d] = MFMA32(pa, __builtin_bit_cast(bf16x8, vf[j & 1][d]), o[d]);
;                   __builtin_amdgcn_sched_barrier(0);
;               } }
.LBB0_911:
	v_sub_f32_e32 v242, v72, v222
	v_sub_f32_e32 v243, v73, v222
	v_sub_f32_e32 v244, v74, v222
	v_exp_f32_e32 v242, v242
	v_sub_f32_e32 v245, v75, v222
	v_exp_f32_e32 v243, v243
	v_sub_f32_e32 v246, v76, v222
	v_exp_f32_e32 v244, v244
	v_sub_f32_e32 v247, v77, v222
	v_exp_f32_e32 v245, v245
	v_sub_f32_e32 v248, v78, v222
	v_exp_f32_e32 v246, v246
	v_sub_f32_e32 v249, v79, v222
	v_exp_f32_e32 v247, v247
	v_exp_f32_e32 v248, v248
	v_exp_f32_e32 v249, v249
	v_cvt_pk_bf16_f32 v232, v242, v243
	v_cvt_pk_bf16_f32 v233, v244, v245
	v_cvt_pk_bf16_f32 v234, v246, v247
	v_cvt_pk_bf16_f32 v235, v248, v249
	v_add_f32_e32 v242, v242, v243
	v_add_f32_e32 v244, v244, v245
	v_add_f32_e32 v246, v246, v247
	v_add_f32_e32 v248, v248, v249
	v_add_f32_e32 v242, v242, v244
	v_add_f32_e32 v246, v246, v248
	v_add_f32_e32 v241, v242, v246
	v_sub_f32_e32 v242, v64, v222
	v_sub_f32_e32 v243, v65, v222
	v_sub_f32_e32 v244, v66, v222
	v_exp_f32_e32 v242, v242
	v_sub_f32_e32 v245, v67, v222
	v_exp_f32_e32 v243, v243
	v_sub_f32_e32 v246, v68, v222
	v_exp_f32_e32 v244, v244
	v_sub_f32_e32 v247, v69, v222
	v_exp_f32_e32 v245, v245
	v_sub_f32_e32 v248, v70, v222
	v_exp_f32_e32 v246, v246
	v_sub_f32_e32 v249, v71, v222
	v_exp_f32_e32 v247, v247
	v_exp_f32_e32 v248, v248
	v_exp_f32_e32 v249, v249
	v_cvt_pk_bf16_f32 v64, v242, v243
	v_cvt_pk_bf16_f32 v65, v244, v245
	v_cvt_pk_bf16_f32 v66, v246, v247
	v_cvt_pk_bf16_f32 v67, v248, v249
	v_add_f32_e32 v242, v242, v243
	v_add_f32_e32 v244, v244, v245
	v_add_f32_e32 v246, v246, v247
	v_add_f32_e32 v248, v248, v249
	v_add_f32_e32 v242, v242, v244
	v_add_f32_e32 v246, v246, v248
	v_add_f32_e32 v242, v242, v246
	v_add_f32_e32 v241, v241, v242
	v_sub_f32_e32 v242, v80, v222
	v_sub_f32_e32 v243, v81, v222
	v_sub_f32_e32 v244, v82, v222
	v_exp_f32_e32 v242, v242
	v_sub_f32_e32 v245, v83, v222
	v_exp_f32_e32 v243, v243
	v_sub_f32_e32 v246, v84, v222
	v_exp_f32_e32 v244, v244
	v_sub_f32_e32 v247, v85, v222
	v_exp_f32_e32 v245, v245
	v_sub_f32_e32 v248, v86, v222
	v_exp_f32_e32 v246, v246
	v_sub_f32_e32 v249, v87, v222
	v_exp_f32_e32 v247, v247
	v_exp_f32_e32 v248, v248
	v_exp_f32_e32 v249, v249
	v_cvt_pk_bf16_f32 v72, v242, v243
	v_cvt_pk_bf16_f32 v73, v244, v245
	v_cvt_pk_bf16_f32 v74, v246, v247
	v_cvt_pk_bf16_f32 v75, v248, v249
	v_add_f32_e32 v242, v242, v243
	v_add_f32_e32 v244, v244, v245
	v_add_f32_e32 v246, v246, v247
	v_add_f32_e32 v248, v248, v249
	v_add_f32_e32 v242, v242, v244
	v_add_f32_e32 v246, v246, v248
	v_add_f32_e32 v242, v242, v246
	v_add_f32_e32 v241, v241, v242
	v_sub_f32_e32 v242, v88, v222
	v_sub_f32_e32 v243, v89, v222
	v_sub_f32_e32 v244, v90, v222
	v_exp_f32_e32 v242, v242
	v_sub_f32_e32 v245, v91, v222
	v_exp_f32_e32 v243, v243
	v_sub_f32_e32 v246, v92, v222
	v_exp_f32_e32 v244, v244
	v_sub_f32_e32 v247, v93, v222
	v_exp_f32_e32 v245, v245
	v_sub_f32_e32 v248, v94, v222
	v_exp_f32_e32 v246, v246
	v_sub_f32_e32 v249, v95, v222
	v_exp_f32_e32 v247, v247
	v_exp_f32_e32 v248, v248
	v_exp_f32_e32 v249, v249
	s_mul_i32 s0, s16, 0x4800
	v_add_u32_e32 v240, s0, v217
	ds_read_b128 v[76:79], v240 offset:51200
	ds_read_b128 v[80:83], v240 offset:51232
	ds_read_b128 v[84:87], v240 offset:55808
	ds_read_b128 v[88:91], v240 offset:55840
	ds_read_b128 v[92:95], v240 offset:60416
	ds_read_b128 v[166:169], v240 offset:60448
	ds_read_b128 v[224:227], v240 offset:65024
	ds_read_b128 v[228:231], v240 offset:65056
	v_cvt_pk_bf16_f32 v68, v242, v243
	v_cvt_pk_bf16_f32 v69, v244, v245
	v_cvt_pk_bf16_f32 v70, v246, v247
	v_cvt_pk_bf16_f32 v71, v248, v249
	v_add_f32_e32 v242, v242, v243
	v_add_f32_e32 v244, v244, v245
	v_add_f32_e32 v246, v246, v247
	v_add_f32_e32 v248, v248, v249
	v_add_f32_e32 v242, v242, v244
	v_add_f32_e32 v246, v246, v248
	v_add_f32_e32 v242, v242, v246
	v_add_f32_e32 v241, v241, v242
	s_waitcnt lgkmcnt(7)
	v_mfma_f32_32x32x16_bf16 v[0:15], v[72:75], v[76:79], v[0:15]
	s_waitcnt lgkmcnt(5)
	v_mfma_f32_32x32x16_bf16 v[48:63], v[72:75], v[84:87], v[48:63]
	s_waitcnt lgkmcnt(3)
	v_mfma_f32_32x32x16_bf16 v[32:47], v[72:75], v[92:95], v[32:47]
	s_waitcnt lgkmcnt(1)
	v_mfma_f32_32x32x16_bf16 v[16:31], v[72:75], v[224:227], v[16:31]
	ds_read_b128 v[72:75], v240 offset:51264
	ds_read_b128 v[76:79], v240 offset:55872
	ds_read_b128 v[84:87], v240 offset:60480
	ds_read_b128 v[92:95], v240 offset:65088
	v_mfma_f32_32x32x16_bf16 v[0:15], v[68:71], v[80:83], v[0:15]
	v_mfma_f32_32x32x16_bf16 v[48:63], v[68:71], v[88:91], v[48:63]
	v_mfma_f32_32x32x16_bf16 v[32:47], v[68:71], v[166:169], v[32:47]
	s_waitcnt lgkmcnt(4)
	v_mfma_f32_32x32x16_bf16 v[16:31], v[68:71], v[228:231], v[16:31]
	ds_read_b128 v[68:71], v240 offset:51296
	ds_read_b128 v[80:83], v240 offset:55904
	ds_read_b128 v[88:91], v240 offset:60512
	ds_read_b128 v[166:169], v240 offset:65120
	s_waitcnt lgkmcnt(7)
	v_mfma_f32_32x32x16_bf16 v[0:15], v[64:67], v[72:75], v[0:15]
	s_waitcnt lgkmcnt(6)
	v_mfma_f32_32x32x16_bf16 v[48:63], v[64:67], v[76:79], v[48:63]
	s_waitcnt lgkmcnt(5)
	v_mfma_f32_32x32x16_bf16 v[32:47], v[64:67], v[84:87], v[32:47]
	s_waitcnt lgkmcnt(4)
	v_mfma_f32_32x32x16_bf16 v[16:31], v[64:67], v[92:95], v[16:31]
	s_waitcnt lgkmcnt(3)
	v_mfma_f32_32x32x16_bf16 v[0:15], v[232:235], v[68:71], v[0:15]
	s_waitcnt lgkmcnt(2)
	v_mfma_f32_32x32x16_bf16 v[48:63], v[232:235], v[80:83], v[48:63]
	s_waitcnt lgkmcnt(1)
	v_mfma_f32_32x32x16_bf16 v[32:47], v[232:235], v[88:91], v[32:47]
	s_waitcnt lgkmcnt(0)
	v_mfma_f32_32x32x16_bf16 v[16:31], v[232:235], v[166:169], v[16:31]
	v_add_f32_e32 v191, v191, v241
